# EpiHalo: the eight row-norm loads issued together up front instead of one per block behind a full drain
# baseline (speedup 1.0000x reference)
;     __device__ __forceinline__ void operator()(const f32x4 (&acc)[2][2][4][2], const Unit& u, int wr, int wc, int fr, int fq) const {
;     ...
;         for (int ai = 0; ai < 2; ++ai)
; #pragma unroll
;             for (int m = 0; m < 4; ++m) {
;                 const int hr = u.pm * 256 + ai * 128 + wr * 64 + m * 16 + fr;
;                 const int orig = 32 * hr - 31 * (hr & 1) - 2;
;                 const float rs = orig >= 0 ? rsqrtf(SS[orig] * (1.0f / D) + EPS) : 0.f;
; #pragma unroll
;                 for (int bj = 0; bj < 2; ++bj) {
;                     const int col0 = u.pn * 256 + bj * 128 + wc * 32 + fq * 8;
;                     float* p = HALO + (size_t)hr * FF2 + col0;
;                     const f32x4 h0 = acc[ai][bj][m][0] * rs, h1 = acc[ai][bj][m][1] * rs;
;                     asm volatile("global_store_dwordx4 %0, %1, off sc1\n\ts_nop 1" :: "v"(p), "v"(h0) : "memory");
;                     asm volatile("global_store_dwordx4 %0, %1, off offset:16 sc1\n\ts_nop 1" :: "v"(p), "v"(h1) : "memory");
;                 }
.LBB0_669:
	s_lshl_b32 s23, s46, 8
	v_mov_b32_e32 v241, 0
	v_add_u32_e32 v240, s23, v147
	v_lshl_add_u32 v240, v240, 5, v149
	v_lshl_add_u64 v[242:243], v[240:241], 2, s[10:11]
	global_load_dword v248, v[242:243], off offset:-8
	v_add_u32_e32 v240, s23, v150
	v_lshl_add_u32 v240, v240, 5, v149
	v_lshl_add_u64 v[242:243], v[240:241], 2, s[10:11]
	global_load_dword v249, v[242:243], off offset:-8
	v_add_u32_e32 v240, s23, v151
	v_lshl_add_u32 v240, v240, 5, v149
	v_lshl_add_u64 v[242:243], v[240:241], 2, s[10:11]
	global_load_dword v250, v[242:243], off offset:-8
	v_add_u32_e32 v240, s23, v153
	v_lshl_add_u32 v240, v240, 5, v149
	v_lshl_add_u64 v[242:243], v[240:241], 2, s[10:11]
	global_load_dword v251, v[242:243], off offset:-8
	v_add_u32_e32 v240, s23, v147
	v_add_u32_e32 v240, 0x80, v240
	v_lshl_add_u32 v240, v240, 5, v149
	v_lshl_add_u64 v[242:243], v[240:241], 2, s[10:11]
	global_load_dword v252, v[242:243], off offset:-8
	v_add_u32_e32 v240, s23, v147
	v_add_u32_e32 v240, 0x90, v240
	v_lshl_add_u32 v240, v240, 5, v149
	v_lshl_add_u64 v[242:243], v[240:241], 2, s[10:11]
	global_load_dword v253, v[242:243], off offset:-8
	v_add_u32_e32 v240, s23, v147
	v_add_u32_e32 v240, 0xa0, v240
	v_lshl_add_u32 v240, v240, 5, v149
	v_lshl_add_u64 v[242:243], v[240:241], 2, s[10:11]
	global_load_dword v254, v[242:243], off offset:-8
	v_add_u32_e32 v240, s23, v147
	v_add_u32_e32 v240, 0xb0, v240
	v_lshl_add_u32 v240, v240, 5, v149
	v_lshl_add_u64 v[242:243], v[240:241], 2, s[10:11]
	global_load_dword v255, v[242:243], off offset:-8
	s_waitcnt vmcnt(0)
	v_add_u32_e32 v164, s23, v147
	v_lshl_add_u32 v136, v164, 5, v149
	v_cmp_lt_i32_e32 vcc, 1, v136
	v_mov_b32_e32 v144, 0
	v_mov_b32_e32 v146, 0
	s_and_saveexec_b64 s[46:47], vcc
	s_cbranch_execz .LBB0_671
	v_lshl_add_u64 v[142:143], v[136:137], 2, s[10:11]
	v_mov_b32_e32 v136, v248
	v_fmamk_f32 v136, v136, 0x3a800000, v163
	v_mul_f32_e32 v142, 0x4b800000, v136
	v_cmp_gt_f32_e32 vcc, s60, v136
	s_nop 1
	v_cndmask_b32_e32 v136, v136, v142, vcc
	v_rsq_f32_e32 v136, v136
	s_nop 0
	v_mul_f32_e32 v142, 0x45800000, v136
	v_cndmask_b32_e32 v146, v136, v142, vcc
.LBB0_671:
	s_or_b64 exec, exec, s[46:47]
	v_lshl_or_b32 v142, s44, 8, v159
	v_mov_b64_e32 v[166:167], s[12:13]
	v_mad_i64_i32 v[166:167], s[44:45], v164, s61, v[166:167]
	v_ashrrev_i32_e32 v143, 31, v142
	v_lshl_add_u64 v[166:167], v[142:143], 2, v[166:167]
	v_pk_mul_f32 v[126:127], v[126:127], v[146:147] op_sel_hi:[1,0]
	v_pk_mul_f32 v[124:125], v[124:125], v[146:147] op_sel_hi:[1,0]
	v_pk_mul_f32 v[122:123], v[122:123], v[146:147] op_sel_hi:[1,0]
	global_store_dwordx4 v[166:167], v[124:127], off sc1
	s_nop 1
	v_pk_mul_f32 v[120:121], v[120:121], v[146:147] op_sel_hi:[1,0]
	v_pk_mul_f32 v[118:119], v[118:119], v[146:147] op_sel_hi:[1,0]
	global_store_dwordx4 v[166:167], v[120:123], off offset:16 sc1
	s_nop 1
	v_lshl_add_u64 v[120:121], v[166:167], 0, s[20:21]
	v_pk_mul_f32 v[116:117], v[116:117], v[146:147] op_sel_hi:[1,0]
	v_pk_mul_f32 v[112:113], v[112:113], v[146:147] op_sel_hi:[1,0]
	global_store_dwordx4 v[120:121], v[116:119], off sc1
	s_nop 1
	v_pk_mul_f32 v[114:115], v[114:115], v[146:147] op_sel_hi:[1,0]
	s_nop 0
	global_store_dwordx4 v[120:121], v[112:115], off offset:16 sc1
	s_nop 1
	v_add_u32_e32 v112, s23, v150
	v_lshl_add_u32 v136, v112, 5, v149
	v_cmp_lt_i32_e32 vcc, 1, v136
	s_and_saveexec_b64 s[44:45], vcc
	s_cbranch_execz .LBB0_673
	v_lshl_add_u64 v[114:115], v[136:137], 2, s[10:11]
	v_mov_b32_e32 v113, v249
	v_fmamk_f32 v113, v113, 0x3a800000, v163
	v_mul_f32_e32 v114, 0x4b800000, v113
	v_cmp_gt_f32_e32 vcc, s60, v113
	s_nop 1
	v_cndmask_b32_e32 v113, v113, v114, vcc
	v_rsq_f32_e32 v113, v113
	s_nop 0
	v_mul_f32_e32 v114, 0x45800000, v113
	v_cndmask_b32_e32 v144, v113, v114, vcc
.LBB0_673:
	s_or_b64 exec, exec, s[44:45]
	v_mov_b64_e32 v[114:115], s[12:13]
	v_mad_i64_i32 v[112:113], s[44:45], v112, s61, v[114:115]
	v_lshl_add_u64 v[112:113], v[142:143], 2, v[112:113]
	v_pk_mul_f32 v[110:111], v[110:111], v[144:145] op_sel_hi:[1,0]
	v_pk_mul_f32 v[108:109], v[108:109], v[144:145] op_sel_hi:[1,0]
	v_pk_mul_f32 v[106:107], v[106:107], v[144:145] op_sel_hi:[1,0]
	global_store_dwordx4 v[112:113], v[108:111], off sc1
	s_nop 1
	v_pk_mul_f32 v[104:105], v[104:105], v[144:145] op_sel_hi:[1,0]
	v_pk_mul_f32 v[102:103], v[102:103], v[144:145] op_sel_hi:[1,0]
	global_store_dwordx4 v[112:113], v[104:107], off offset:16 sc1
	s_nop 1
	v_lshl_add_u64 v[104:105], v[112:113], 0, s[20:21]
	v_pk_mul_f32 v[100:101], v[100:101], v[144:145] op_sel_hi:[1,0]
	v_pk_mul_f32 v[96:97], v[96:97], v[144:145] op_sel_hi:[1,0]
	global_store_dwordx4 v[104:105], v[100:103], off sc1
	s_nop 1
	v_pk_mul_f32 v[98:99], v[98:99], v[144:145] op_sel_hi:[1,0]
	s_nop 0
	global_store_dwordx4 v[104:105], v[96:99], off offset:16 sc1
	s_nop 1
	v_add_u32_e32 v97, s23, v151
	v_lshl_add_u32 v136, v97, 5, v149
	v_cmp_lt_i32_e32 vcc, 1, v136
	v_mov_b32_e32 v96, 0
	v_mov_b32_e32 v98, 0
	s_and_saveexec_b64 s[44:45], vcc
	s_cbranch_execz .LBB0_675
	v_lshl_add_u64 v[98:99], v[136:137], 2, s[10:11]
	v_mov_b32_e32 v98, v250
	v_fmamk_f32 v98, v98, 0x3a800000, v163
	v_mul_f32_e32 v99, 0x4b800000, v98
	v_cmp_gt_f32_e32 vcc, s60, v98
	s_nop 1
	v_cndmask_b32_e32 v98, v98, v99, vcc
	v_rsq_f32_e32 v98, v98
	s_nop 0
	v_mul_f32_e32 v99, 0x45800000, v98
	v_cndmask_b32_e32 v98, v98, v99, vcc
;     __device__ __forceinline__ void operator()(const f32x4 (&acc)[2][2][4][2], const Unit& u, int wr, int wc, int fr, int fq) const {
;     ...
;                 const int hr = u.pm * 256 + ai * 128 + wr * 64 + m * 16 + fr;
;                 const int orig = 32 * hr - 31 * (hr & 1) - 2;
;                 const float rs = orig >= 0 ? rsqrtf(SS[orig] * (1.0f / D) + EPS) : 0.f;
; #pragma unroll
;                 for (int bj = 0; bj < 2; ++bj) {
;                     const int col0 = u.pn * 256 + bj * 128 + wc * 32 + fq * 8;
;                     float* p = HALO + (size_t)hr * FF2 + col0;
;                     const f32x4 h0 = acc[ai][bj][m][0] * rs, h1 = acc[ai][bj][m][1] * rs;
;                     asm volatile("global_store_dwordx4 %0, %1, off sc1\n\ts_nop 1" :: "v"(p), "v"(h0) : "memory");
;                     asm volatile("global_store_dwordx4 %0, %1, off offset:16 sc1\n\ts_nop 1" :: "v"(p), "v"(h1) : "memory");
;                 }
.LBB0_675:
	s_or_b64 exec, exec, s[44:45]
	v_mov_b64_e32 v[100:101], s[12:13]
	v_mad_i64_i32 v[100:101], s[44:45], v97, s61, v[100:101]
	v_lshl_add_u64 v[100:101], v[142:143], 2, v[100:101]
	v_pk_mul_f32 v[94:95], v[94:95], v[98:99] op_sel_hi:[1,0]
	v_pk_mul_f32 v[92:93], v[92:93], v[98:99] op_sel_hi:[1,0]
	v_pk_mul_f32 v[90:91], v[90:91], v[98:99] op_sel_hi:[1,0]
	global_store_dwordx4 v[100:101], v[92:95], off sc1
	s_nop 1
	v_pk_mul_f32 v[88:89], v[88:89], v[98:99] op_sel_hi:[1,0]
	v_pk_mul_f32 v[86:87], v[86:87], v[98:99] op_sel_hi:[1,0]
	global_store_dwordx4 v[100:101], v[88:91], off offset:16 sc1
	s_nop 1
	v_lshl_add_u64 v[88:89], v[100:101], 0, s[20:21]
	v_pk_mul_f32 v[84:85], v[84:85], v[98:99] op_sel_hi:[1,0]
	v_pk_mul_f32 v[80:81], v[80:81], v[98:99] op_sel_hi:[1,0]
	global_store_dwordx4 v[88:89], v[84:87], off sc1
	s_nop 1
	v_pk_mul_f32 v[82:83], v[82:83], v[98:99] op_sel_hi:[1,0]
	s_nop 0
	global_store_dwordx4 v[88:89], v[80:83], off offset:16 sc1
	s_nop 1
	v_add_u32_e32 v80, s23, v153
	v_lshl_add_u32 v136, v80, 5, v149
	v_cmp_lt_i32_e32 vcc, 1, v136
	s_and_saveexec_b64 s[44:45], vcc
	s_cbranch_execz .LBB0_677
	v_lshl_add_u64 v[82:83], v[136:137], 2, s[10:11]
	v_mov_b32_e32 v81, v251
	v_fmamk_f32 v81, v81, 0x3a800000, v163
	v_mul_f32_e32 v82, 0x4b800000, v81
	v_cmp_gt_f32_e32 vcc, s60, v81
	s_nop 1
	v_cndmask_b32_e32 v81, v81, v82, vcc
	v_rsq_f32_e32 v81, v81
	s_nop 0
	v_mul_f32_e32 v82, 0x45800000, v81
	v_cndmask_b32_e32 v96, v81, v82, vcc
.LBB0_677:
	s_or_b64 exec, exec, s[44:45]
	v_mov_b64_e32 v[82:83], s[12:13]
	v_mad_i64_i32 v[80:81], s[44:45], v80, s61, v[82:83]
	v_lshl_add_u64 v[80:81], v[142:143], 2, v[80:81]
	v_pk_mul_f32 v[78:79], v[78:79], v[96:97] op_sel_hi:[1,0]
	v_pk_mul_f32 v[76:77], v[76:77], v[96:97] op_sel_hi:[1,0]
	v_pk_mul_f32 v[74:75], v[74:75], v[96:97] op_sel_hi:[1,0]
	global_store_dwordx4 v[80:81], v[76:79], off sc1
	s_nop 1
	v_pk_mul_f32 v[72:73], v[72:73], v[96:97] op_sel_hi:[1,0]
	v_pk_mul_f32 v[70:71], v[70:71], v[96:97] op_sel_hi:[1,0]
	global_store_dwordx4 v[80:81], v[72:75], off offset:16 sc1
	s_nop 1
	v_lshl_add_u64 v[72:73], v[80:81], 0, s[20:21]
	v_pk_mul_f32 v[68:69], v[68:69], v[96:97] op_sel_hi:[1,0]
	v_pk_mul_f32 v[64:65], v[64:65], v[96:97] op_sel_hi:[1,0]
	global_store_dwordx4 v[72:73], v[68:71], off sc1
	s_nop 1
	v_pk_mul_f32 v[66:67], v[66:67], v[96:97] op_sel_hi:[1,0]
	s_nop 0
	global_store_dwordx4 v[72:73], v[64:67], off offset:16 sc1
	s_nop 1
	v_add_u32_e32 v65, 0x80, v164
	v_lshl_add_u32 v136, v65, 5, v149
	v_cmp_lt_i32_e32 vcc, 1, v136
	v_mov_b32_e32 v64, 0
	v_mov_b32_e32 v66, 0
	s_and_saveexec_b64 s[44:45], vcc
	s_cbranch_execz .LBB0_679
	v_lshl_add_u64 v[66:67], v[136:137], 2, s[10:11]
	v_mov_b32_e32 v66, v252
	v_fmamk_f32 v66, v66, 0x3a800000, v163
	v_mul_f32_e32 v67, 0x4b800000, v66
	v_cmp_gt_f32_e32 vcc, s60, v66
	s_nop 1
	v_cndmask_b32_e32 v66, v66, v67, vcc
	v_rsq_f32_e32 v66, v66
	s_nop 0
	v_mul_f32_e32 v67, 0x45800000, v66
	v_cndmask_b32_e32 v66, v66, v67, vcc
;     __device__ __forceinline__ void operator()(const f32x4 (&acc)[2][2][4][2], const Unit& u, int wr, int wc, int fr, int fq) const {
;     ...
;                 const int hr = u.pm * 256 + ai * 128 + wr * 64 + m * 16 + fr;
;                 const int orig = 32 * hr - 31 * (hr & 1) - 2;
;                 const float rs = orig >= 0 ? rsqrtf(SS[orig] * (1.0f / D) + EPS) : 0.f;
; #pragma unroll
;                 for (int bj = 0; bj < 2; ++bj) {
;                     const int col0 = u.pn * 256 + bj * 128 + wc * 32 + fq * 8;
;                     float* p = HALO + (size_t)hr * FF2 + col0;
;                     const f32x4 h0 = acc[ai][bj][m][0] * rs, h1 = acc[ai][bj][m][1] * rs;
;                     asm volatile("global_store_dwordx4 %0, %1, off sc1\n\ts_nop 1" :: "v"(p), "v"(h0) : "memory");
;                     asm volatile("global_store_dwordx4 %0, %1, off offset:16 sc1\n\ts_nop 1" :: "v"(p), "v"(h1) : "memory");
;                 }
.LBB0_679:
	s_or_b64 exec, exec, s[44:45]
	v_mov_b64_e32 v[68:69], s[12:13]
	v_mad_i64_i32 v[68:69], s[44:45], v65, s61, v[68:69]
	v_lshl_add_u64 v[68:69], v[142:143], 2, v[68:69]
	v_pk_mul_f32 v[62:63], v[62:63], v[66:67] op_sel_hi:[1,0]
	v_pk_mul_f32 v[60:61], v[60:61], v[66:67] op_sel_hi:[1,0]
	v_pk_mul_f32 v[58:59], v[58:59], v[66:67] op_sel_hi:[1,0]
	global_store_dwordx4 v[68:69], v[60:63], off sc1
	s_nop 1
	v_pk_mul_f32 v[56:57], v[56:57], v[66:67] op_sel_hi:[1,0]
	v_pk_mul_f32 v[54:55], v[54:55], v[66:67] op_sel_hi:[1,0]
	global_store_dwordx4 v[68:69], v[56:59], off offset:16 sc1
	s_nop 1
	v_lshl_add_u64 v[56:57], v[68:69], 0, s[20:21]
	v_pk_mul_f32 v[52:53], v[52:53], v[66:67] op_sel_hi:[1,0]
	v_pk_mul_f32 v[48:49], v[48:49], v[66:67] op_sel_hi:[1,0]
	global_store_dwordx4 v[56:57], v[52:55], off sc1
	s_nop 1
	v_pk_mul_f32 v[50:51], v[50:51], v[66:67] op_sel_hi:[1,0]
	s_nop 0
	global_store_dwordx4 v[56:57], v[48:51], off offset:16 sc1
	s_nop 1
	v_add_u32_e32 v48, 0x90, v164
	v_lshl_add_u32 v136, v48, 5, v149
	v_cmp_lt_i32_e32 vcc, 1, v136
	s_and_saveexec_b64 s[44:45], vcc
	s_cbranch_execz .LBB0_681
	v_lshl_add_u64 v[50:51], v[136:137], 2, s[10:11]
	v_mov_b32_e32 v49, v253
	v_fmamk_f32 v49, v49, 0x3a800000, v163
	v_mul_f32_e32 v50, 0x4b800000, v49
	v_cmp_gt_f32_e32 vcc, s60, v49
	s_nop 1
	v_cndmask_b32_e32 v49, v49, v50, vcc
	v_rsq_f32_e32 v49, v49
	s_nop 0
	v_mul_f32_e32 v50, 0x45800000, v49
	v_cndmask_b32_e32 v64, v49, v50, vcc
.LBB0_681:
	s_or_b64 exec, exec, s[44:45]
	v_mov_b64_e32 v[50:51], s[12:13]
	v_mad_i64_i32 v[48:49], s[44:45], v48, s61, v[50:51]
	v_lshl_add_u64 v[48:49], v[142:143], 2, v[48:49]
	v_pk_mul_f32 v[46:47], v[46:47], v[64:65] op_sel_hi:[1,0]
	v_pk_mul_f32 v[44:45], v[44:45], v[64:65] op_sel_hi:[1,0]
	v_pk_mul_f32 v[42:43], v[42:43], v[64:65] op_sel_hi:[1,0]
	global_store_dwordx4 v[48:49], v[44:47], off sc1
	s_nop 1
	v_pk_mul_f32 v[40:41], v[40:41], v[64:65] op_sel_hi:[1,0]
	v_pk_mul_f32 v[38:39], v[38:39], v[64:65] op_sel_hi:[1,0]
	global_store_dwordx4 v[48:49], v[40:43], off offset:16 sc1
	s_nop 1
	v_lshl_add_u64 v[40:41], v[48:49], 0, s[20:21]
	v_pk_mul_f32 v[36:37], v[36:37], v[64:65] op_sel_hi:[1,0]
	v_pk_mul_f32 v[32:33], v[32:33], v[64:65] op_sel_hi:[1,0]
	global_store_dwordx4 v[40:41], v[36:39], off sc1
	s_nop 1
	v_pk_mul_f32 v[34:35], v[34:35], v[64:65] op_sel_hi:[1,0]
	s_nop 0
	global_store_dwordx4 v[40:41], v[32:35], off offset:16 sc1
	s_nop 1
	v_add_u32_e32 v33, 0xa0, v164
	v_lshl_add_u32 v136, v33, 5, v149
	v_cmp_lt_i32_e32 vcc, 1, v136
	v_mov_b32_e32 v32, 0
	v_mov_b32_e32 v34, 0
	s_and_saveexec_b64 s[44:45], vcc
	s_cbranch_execz .LBB0_683
	v_lshl_add_u64 v[34:35], v[136:137], 2, s[10:11]
	v_mov_b32_e32 v34, v254
	v_fmamk_f32 v34, v34, 0x3a800000, v163
	v_mul_f32_e32 v35, 0x4b800000, v34
	v_cmp_gt_f32_e32 vcc, s60, v34
	s_nop 1
	v_cndmask_b32_e32 v34, v34, v35, vcc
	v_rsq_f32_e32 v34, v34
	s_nop 0
	v_mul_f32_e32 v35, 0x45800000, v34
	v_cndmask_b32_e32 v34, v34, v35, vcc
.LBB0_683:
	s_or_b64 exec, exec, s[44:45]
	v_mov_b64_e32 v[36:37], s[12:13]
	v_mad_i64_i32 v[36:37], s[44:45], v33, s61, v[36:37]
	v_lshl_add_u64 v[36:37], v[142:143], 2, v[36:37]
	v_pk_mul_f32 v[30:31], v[30:31], v[34:35] op_sel_hi:[1,0]
	v_pk_mul_f32 v[28:29], v[28:29], v[34:35] op_sel_hi:[1,0]
	v_pk_mul_f32 v[26:27], v[26:27], v[34:35] op_sel_hi:[1,0]
	global_store_dwordx4 v[36:37], v[28:31], off sc1
	s_nop 1
	v_pk_mul_f32 v[24:25], v[24:25], v[34:35] op_sel_hi:[1,0]
	v_pk_mul_f32 v[22:23], v[22:23], v[34:35] op_sel_hi:[1,0]
	global_store_dwordx4 v[36:37], v[24:27], off offset:16 sc1
	s_nop 1
	v_lshl_add_u64 v[24:25], v[36:37], 0, s[20:21]
	v_pk_mul_f32 v[20:21], v[20:21], v[34:35] op_sel_hi:[1,0]
	v_pk_mul_f32 v[16:17], v[16:17], v[34:35] op_sel_hi:[1,0]
	global_store_dwordx4 v[24:25], v[20:23], off sc1
	s_nop 1
	v_pk_mul_f32 v[18:19], v[18:19], v[34:35] op_sel_hi:[1,0]
	s_nop 0
	global_store_dwordx4 v[24:25], v[16:19], off offset:16 sc1
	s_nop 1
	v_add_u32_e32 v16, 0xb0, v164
	v_lshl_add_u32 v136, v16, 5, v149
	v_cmp_lt_i32_e32 vcc, 1, v136
	s_and_saveexec_b64 s[44:45], vcc
	s_cbranch_execz .LBB0_685
	v_lshl_add_u64 v[18:19], v[136:137], 2, s[10:11]
	v_mov_b32_e32 v17, v255
	v_fmamk_f32 v17, v17, 0x3a800000, v163
	v_mul_f32_e32 v18, 0x4b800000, v17
	v_cmp_gt_f32_e32 vcc, s60, v17
	s_nop 1
	v_cndmask_b32_e32 v17, v17, v18, vcc
	v_rsq_f32_e32 v17, v17
	s_nop 0
	v_mul_f32_e32 v18, 0x45800000, v17
	v_cndmask_b32_e32 v32, v17, v18, vcc
